# final RMSNorm: next rows requested before the current rows' stores so the counted wait does not drain the stores
# speedup vs baseline: 1.0005x; 1.0005x over previous
; #define GAS __attribute__((address_space(1)))
; #define LDPTR(i) ({ volatile LAS unsigned* p_ = (volatile LAS unsigned*)(lds + 131072 + 8 * (i)); const unsigned lo_ = __builtin_amdgcn_readfirstlane(p_[0]), hi_ = __builtin_amdgcn_readfirstlane(p_[1]); (const GAS float*)(((unsigned long long)hi_ << 32) | lo_); })
; __global__ void __launch_bounds__(512, 2) mk_fwd(Args a) {
;     ...
;     {
;         int tid13 = threadIdx.x; asm volatile("" : "+v"(tid13)); const int lane = tid13 & 63;
;         const GAS float* parts = (const GAS float*)(ws + WS_PARTD); const GAS float* fingp = LDPTR(6);
;         const GAS bf16* hbp = (const GAS bf16*)(ws + WS_HB);
;         f32x4 gg[4];
; #pragma unroll
;         for (int j = 0; j < 4; ++j) gg[j] = ((const GAS f32x4*)fingp)[lane + 64 * j];
;         for (int m0 = 2 * (vb * 8 + wave); m0 < NT; m0 += 2 * G * 8) {
;             u32x2 hw[2][4]; float sp[2];
; #pragma unroll
;             for (int rr = 0; rr < 2; ++rr) { const int m = m0 + rr; sp[rr] = lane < 16 ? parts[(size_t)m * 16 + lane] : 0.f; const GAS u32x2* hr = (const GAS u32x2*)(hbp + (size_t)m * DM) + lane;
; #pragma unroll
;                 for (int j = 0; j < 4; ++j) hw[rr][j] = __builtin_nontemporal_load(&hr[64 * j]); }
.LBB0_1799:
	s_or_b64 exec, exec, s[0:1]
	s_add_i32 s0, 0, 0x20030
	v_mov_b32_e32 v0, s0
	s_add_i32 s0, 0, 0x20034
	v_mov_b32_e32 v1, s0
	s_waitcnt lgkmcnt(0)
	s_barrier
	ds_read_b32 v0, v0
	ds_read_b32 v1, v1
	s_lshl_b32 s1, s77, 4
	s_add_i32 s4, s85, s1
	s_cmpk_gt_i32 s4, 0x7fff
	s_waitcnt lgkmcnt(0)
	v_readfirstlane_b32 s0, v0
	v_readfirstlane_b32 s1, v1
	s_cbranch_scc1 .LBB0_1806
	v_and_b32_e32 v22, 63, v252
	v_lshlrev_b32_e32 v20, 4, v22
	s_nop 1
	global_load_dwordx4 v[0:3], v20, s[0:1]
	global_load_dwordx4 v[4:7], v20, s[0:1] offset:1024
	global_load_dwordx4 v[8:11], v20, s[0:1] offset:2048
	global_load_dwordx4 v[12:15], v20, s[0:1] offset:3072
	v_xor_b32_e32 v16, 1, v253
	v_cmp_lt_i32_e64 s[2:3], v16, v226
	s_load_dwordx2 s[0:1], s[74:75], 0xd8
	s_ashr_i32 s5, s4, 31
	v_cndmask_b32_e64 v16, v253, v16, s[2:3]
	v_lshlrev_b32_e32 v23, 2, v16
	v_xor_b32_e32 v16, 2, v253
	v_cmp_lt_i32_e64 s[2:3], v16, v226
	s_lshl_b32 s6, s76, 4
	v_mov_b32_e32 v21, 0
	v_cndmask_b32_e64 v16, v253, v16, s[2:3]
	v_lshlrev_b32_e32 v34, 2, v16
	v_xor_b32_e32 v16, 4, v253
	v_cmp_lt_i32_e64 s[2:3], v16, v226
	v_cmp_gt_u32_e32 vcc, 16, v22
	s_mov_b32 s14, 0x3a800000
	v_cndmask_b32_e64 v16, v253, v16, s[2:3]
	v_lshlrev_b32_e32 v35, 2, v16
	v_xor_b32_e32 v16, 8, v253
	v_cmp_lt_i32_e64 s[2:3], v16, v226
	s_nop 1
	v_cndmask_b32_e64 v16, v253, v16, s[2:3]
	v_cmp_lt_i32_e64 s[2:3], v227, v226
	v_lshlrev_b32_e32 v36, 2, v16
	s_nop 0
	v_cndmask_b32_e64 v16, v253, v227, s[2:3]
	v_lshlrev_b32_e32 v37, 2, v16
	v_xor_b32_e32 v16, 32, v253
	v_cmp_lt_i32_e64 s[2:3], v16, v226
	s_nop 1
	v_cndmask_b32_e64 v16, v253, v16, s[2:3]
	s_lshl_b64 s[2:3], s[4:5], 12
	s_waitcnt lgkmcnt(0)
	s_add_u32 s0, s0, s2
	s_addc_u32 s1, s1, s3
	v_lshlrev_b32_e32 v38, 2, v16
	v_lshl_add_u64 v[16:17], s[0:1], 0, v[20:21]
	s_mov_b64 s[0:1], 0x1000
	s_ashr_i32 s7, s6, 31
	v_lshl_add_u64 v[16:17], v[16:17], 0, s[0:1]
	s_lshl_b64 s[8:9], s[6:7], 12
	s_lshl_b64 s[0:1], s[4:5], 6
	s_add_u32 s0, s72, s0
	v_lshlrev_b32_e32 v20, 2, v22
	s_addc_u32 s1, s73, s1
	v_lshl_add_u64 v[18:19], s[0:1], 0, v[20:21]
	s_mov_b64 s[0:1], 0x800040
	v_lshl_add_u64 v[18:19], v[18:19], 0, s[0:1]
	s_lshl_b64 s[10:11], s[6:7], 6
	s_lshl_b64 s[0:1], s[4:5], 11
	s_add_u32 s0, s72, s0
	v_lshlrev_b32_e32 v20, 3, v22
	s_addc_u32 s1, s73, s1
	v_lshl_add_u64 v[20:21], s[0:1], 0, v[20:21]
	s_mov_b64 s[0:1], 0x4400800
	v_lshl_add_u64 v[20:21], v[20:21], 0, s[0:1]
	s_lshl_b64 s[12:13], s[6:7], 11
	v_mov_b32_e32 v22, 0x358637bd
	s_mov_b32 s5, 0x800000
	v_mov_b32_e32 v33, 0
	s_and_saveexec_b64 s[0:1], vcc
	global_load_dword v33, v[18:19], off offset:-64
	s_or_b64 exec, exec, s[0:1]
	global_load_dwordx2 v[30:31], v[20:21], off offset:-2048 nt
	global_load_dwordx2 v[28:29], v[20:21], off offset:-1536 nt
	global_load_dwordx2 v[26:27], v[20:21], off offset:-1024 nt
	global_load_dwordx2 v[24:25], v[20:21], off offset:-512 nt
	v_mov_b32_e32 v32, 0
	s_and_saveexec_b64 s[0:1], vcc
	global_load_dword v32, v[18:19], off
	s_or_b64 exec, exec, s[0:1]
	global_load_dwordx2 v[48:49], v[20:21], off nt
	global_load_dwordx2 v[50:51], v[20:21], off offset:512 nt
	global_load_dwordx2 v[52:53], v[20:21], off offset:1024 nt
	global_load_dwordx2 v[54:55], v[20:21], off offset:1536 nt
	s_waitcnt vmcnt(0)
; #define GAS __attribute__((address_space(1)))
; __global__ void __launch_bounds__(512, 2) mk_fwd(Args a) {
;     ...
;         for (int m0 = 2 * (vb * 8 + wave); m0 < NT; m0 += 2 * G * 8) {
;             u32x2 hw[2][4]; float sp[2];
; #pragma unroll
;             for (int rr = 0; rr < 2; ++rr) { const int m = m0 + rr; sp[rr] = lane < 16 ? parts[(size_t)m * 16 + lane] : 0.f; const GAS u32x2* hr = (const GAS u32x2*)(hbp + (size_t)m * DM) + lane;
; #pragma unroll
;                 for (int j = 0; j < 4; ++j) hw[rr][j] = __builtin_nontemporal_load(&hr[64 * j]); }
; #pragma unroll
;             for (int rr = 0; rr < 2; ++rr) { const int m = m0 + rr; const float s = wave_sum(sp[rr]); const float rs = rsqrtf(s * (1.f / 1024.f) + EPS);
;                 GAS f32x4* o = (GAS f32x4*)(a.out + (size_t)m * DM) + lane;
; #pragma unroll
;                 for (int j = 0; j < 4; ++j) { const u32x2 w = hw[rr][j]; const f32x4 v = {bflo(w.x), bfhi(w.x), bflo(w.y), bfhi(w.y)}; __builtin_nontemporal_store(v * rs * gg[j], &o[64 * j]); } }
;         }
.Lp13_loop:
	s_waitcnt vmcnt(8)
	v_mov_b32_e32 v124, v24
	v_mov_b32_e32 v125, v25
	v_mov_b32_e32 v126, v26
	v_mov_b32_e32 v127, v27
	v_mov_b32_e32 v128, v28
	v_mov_b32_e32 v129, v29
	v_mov_b32_e32 v130, v30
	v_mov_b32_e32 v131, v31
	v_mov_b32_e32 v132, v32
	v_mov_b32_e32 v133, v33
	v_mov_b32_e32 v148, v48
	v_mov_b32_e32 v149, v49
	v_mov_b32_e32 v150, v50
	v_mov_b32_e32 v151, v51
	v_mov_b32_e32 v152, v52
	v_mov_b32_e32 v153, v53
	v_mov_b32_e32 v154, v54
	v_mov_b32_e32 v155, v55
	v_lshl_add_u64 v[18:19], v[18:19], 0, s[10:11]
	v_lshl_add_u64 v[20:21], v[20:21], 0, s[12:13]
	v_mov_b32_e32 v33, 0
	s_and_saveexec_b64 s[0:1], vcc
	global_load_dword v33, v[18:19], off offset:-64
	s_or_b64 exec, exec, s[0:1]
	global_load_dwordx2 v[30:31], v[20:21], off offset:-2048 nt
	global_load_dwordx2 v[28:29], v[20:21], off offset:-1536 nt
	global_load_dwordx2 v[26:27], v[20:21], off offset:-1024 nt
	global_load_dwordx2 v[24:25], v[20:21], off offset:-512 nt
	v_mov_b32_e32 v32, 0
	s_and_saveexec_b64 s[0:1], vcc
	global_load_dword v32, v[18:19], off
	s_or_b64 exec, exec, s[0:1]
	global_load_dwordx2 v[48:49], v[20:21], off nt
	global_load_dwordx2 v[50:51], v[20:21], off offset:512 nt
	global_load_dwordx2 v[52:53], v[20:21], off offset:1024 nt
	global_load_dwordx2 v[54:55], v[20:21], off offset:1536 nt
	ds_bpermute_b32 v41, v23, v133
	ds_bpermute_b32 v40, v23, v132
	v_lshlrev_b32_e32 v56, 16, v124
	v_and_b32_e32 v57, 0xffff0000, v124
	v_lshlrev_b32_e32 v42, 16, v130
	v_and_b32_e32 v43, 0xffff0000, v130
	s_waitcnt lgkmcnt(0)
	v_pk_add_f32 v[132:133], v[132:133], v[40:41]
	ds_bpermute_b32 v41, v34, v133
	ds_bpermute_b32 v40, v34, v132
	v_lshlrev_b32_e32 v130, 16, v131
	v_and_b32_e32 v131, 0xffff0000, v131
	v_lshlrev_b32_e32 v44, 16, v128
	v_and_b32_e32 v45, 0xffff0000, v128
	s_waitcnt lgkmcnt(0)
	v_pk_add_f32 v[132:133], v[132:133], v[40:41]
	ds_bpermute_b32 v41, v35, v133
	ds_bpermute_b32 v40, v35, v132
	v_lshlrev_b32_e32 v128, 16, v129
	v_and_b32_e32 v129, 0xffff0000, v129
	v_lshlrev_b32_e32 v46, 16, v126
	v_and_b32_e32 v47, 0xffff0000, v126
	s_waitcnt lgkmcnt(0)
	v_pk_add_f32 v[132:133], v[132:133], v[40:41]
	ds_bpermute_b32 v41, v36, v133
	ds_bpermute_b32 v40, v36, v132
	v_lshlrev_b32_e32 v126, 16, v127
	v_and_b32_e32 v127, 0xffff0000, v127
	s_add_i32 s4, s4, s6
	s_waitcnt lgkmcnt(0)
	v_pk_add_f32 v[132:133], v[132:133], v[40:41]
	ds_bpermute_b32 v41, v37, v133
	ds_bpermute_b32 v40, v37, v132
	s_cmpk_gt_i32 s4, 0x7fff
	s_waitcnt lgkmcnt(0)
	v_pk_add_f32 v[132:133], v[132:133], v[40:41]
	ds_bpermute_b32 v41, v38, v133
	ds_bpermute_b32 v40, v38, v132
	s_waitcnt lgkmcnt(0)
	v_pk_add_f32 v[132:133], v[132:133], v[40:41]
	s_nop 0
	v_pk_fma_f32 v[132:133], v[132:133], s[14:15], v[22:23] op_sel_hi:[1,0,0]
	s_nop 0
	v_mul_f32_e32 v124, 0x4b800000, v133
	v_cmp_gt_f32_e64 s[0:1], s5, v133
	v_mul_f32_e32 v39, 0x4b800000, v132
	v_cmp_gt_f32_e64 s[2:3], s5, v132
	v_cndmask_b32_e64 v124, v133, v124, s[0:1]
	v_rsq_f32_e32 v133, v124
	v_cndmask_b32_e64 v132, v132, v39, s[2:3]
	v_rsq_f32_e32 v39, v132
	v_lshlrev_b32_e32 v124, 16, v125
	v_mul_f32_e32 v132, 0x45800000, v133
	v_cndmask_b32_e64 v132, v133, v132, s[0:1]
	v_mul_f32_e32 v40, 0x45800000, v39
	v_and_b32_e32 v125, 0xffff0000, v125
	v_cndmask_b32_e64 v58, v39, v40, s[2:3]
	v_pk_mul_f32 v[40:41], v[132:133], v[42:43] op_sel_hi:[0,1]
	v_pk_mul_f32 v[130:131], v[132:133], v[130:131] op_sel_hi:[0,1]
	v_pk_mul_f32 v[42:43], v[132:133], v[44:45] op_sel_hi:[0,1]
	v_pk_mul_f32 v[128:129], v[132:133], v[128:129] op_sel_hi:[0,1]
	v_pk_mul_f32 v[44:45], v[132:133], v[46:47] op_sel_hi:[0,1]
	v_pk_mul_f32 v[46:47], v[132:133], v[126:127] op_sel_hi:[0,1]
	v_pk_mul_f32 v[56:57], v[132:133], v[56:57] op_sel_hi:[0,1]
	v_pk_mul_f32 v[132:133], v[132:133], v[124:125] op_sel_hi:[0,1]
	v_pk_mul_f32 v[126:127], v[2:3], v[130:131]
	v_pk_mul_f32 v[124:125], v[0:1], v[40:41]
	v_pk_mul_f32 v[130:131], v[6:7], v[128:129]
	v_pk_mul_f32 v[128:129], v[4:5], v[42:43]
	v_pk_mul_f32 v[42:43], v[10:11], v[46:47]
	v_pk_mul_f32 v[40:41], v[8:9], v[44:45]
	v_pk_mul_f32 v[46:47], v[14:15], v[132:133]
	v_pk_mul_f32 v[44:45], v[12:13], v[56:57]
	global_store_dwordx4 v[16:17], v[124:127], off offset:-4096 nt
	global_store_dwordx4 v[16:17], v[128:131], off offset:-3072 nt
	global_store_dwordx4 v[16:17], v[40:43], off offset:-2048 nt
	global_store_dwordx4 v[16:17], v[44:47], off offset:-1024 nt
	v_lshlrev_b32_e32 v124, 16, v148
	v_and_b32_e32 v125, 0xffff0000, v148
	v_lshlrev_b32_e32 v126, 16, v149
	v_and_b32_e32 v127, 0xffff0000, v149
	v_pk_mul_f32 v[124:125], v[58:59], v[124:125] op_sel_hi:[0,1]
	v_pk_mul_f32 v[126:127], v[58:59], v[126:127] op_sel_hi:[0,1]
	v_lshlrev_b32_e32 v128, 16, v150
	v_and_b32_e32 v129, 0xffff0000, v150
	v_lshlrev_b32_e32 v130, 16, v151
	v_and_b32_e32 v131, 0xffff0000, v151
	v_pk_mul_f32 v[126:127], v[2:3], v[126:127]
	v_pk_mul_f32 v[124:125], v[0:1], v[124:125]
	global_store_dwordx4 v[16:17], v[124:127], off nt
	s_nop 1
	v_pk_mul_f32 v[124:125], v[58:59], v[128:129] op_sel_hi:[0,1]
	v_pk_mul_f32 v[126:127], v[58:59], v[130:131] op_sel_hi:[0,1]
	v_pk_mul_f32 v[126:127], v[6:7], v[126:127]
	v_pk_mul_f32 v[124:125], v[4:5], v[124:125]
	global_store_dwordx4 v[16:17], v[124:127], off offset:1024 nt
	s_nop 1
	v_lshlrev_b32_e32 v124, 16, v152
	v_and_b32_e32 v125, 0xffff0000, v152
	v_lshlrev_b32_e32 v126, 16, v153
	v_and_b32_e32 v127, 0xffff0000, v153
	v_pk_mul_f32 v[124:125], v[58:59], v[124:125] op_sel_hi:[0,1]
	v_pk_mul_f32 v[126:127], v[58:59], v[126:127] op_sel_hi:[0,1]
	v_pk_mul_f32 v[126:127], v[10:11], v[126:127]
	v_pk_mul_f32 v[124:125], v[8:9], v[124:125]
	global_store_dwordx4 v[16:17], v[124:127], off offset:2048 nt
	s_nop 1
	v_lshlrev_b32_e32 v124, 16, v154
	v_and_b32_e32 v125, 0xffff0000, v154
	v_lshlrev_b32_e32 v126, 16, v155
	v_and_b32_e32 v127, 0xffff0000, v155
	v_pk_mul_f32 v[124:125], v[58:59], v[124:125] op_sel_hi:[0,1]
	v_pk_mul_f32 v[126:127], v[58:59], v[126:127] op_sel_hi:[0,1]
	v_pk_mul_f32 v[126:127], v[14:15], v[126:127]
	v_pk_mul_f32 v[124:125], v[12:13], v[124:125]
	global_store_dwordx4 v[16:17], v[124:127], off offset:3072 nt
	v_lshl_add_u64 v[16:17], v[16:17], 0, s[8:9]
	s_cbranch_scc0 .Lp13_loop
